# grid barrier: one L1 invalidate per CU (registered via HW_ID at start) issued before arrival, instead of one per workgroup
# speedup vs baseline: 1.0480x; 1.0480x over previous
_Z9trunk_fwd6Params:
	s_load_dword s5, s[0:1], 0x110
	v_writelane_b32 v249, s2, 0
	v_writelane_b32 v249, s0, 1
	s_load_dwordx2 s[18:19], s[0:1], 0x100
	s_mov_b32 s4, 0
	s_waitcnt lgkmcnt(0)
	s_cmp_eq_u32 s5, 0
	v_writelane_b32 v249, s1, 2
	s_cbranch_scc1 .LBB0_7
	v_and_b32_e32 v1, 0x3ff, v0
	v_cmp_eq_u32_e32 vcc, 0, v1
	s_and_saveexec_b64 s[0:1], vcc
	s_cbranch_execz .LBB0_3
	s_mov_b64 s[2:3], src_shared_base
	v_mov_b32_e32 v2, 0x12010
	v_mov_b32_e32 v3, s3
	v_mov_b32_e32 v1, 0
	v_writelane_b32 v247, s4, 57
	v_mov_b32_e32 v2, 0x12014
	v_writelane_b32 v247, s4, 58
	s_mov_b32 s6, 1
	v_writelane_b32 v247, s6, 61
	v_writelane_b32 v247, s4, 62
.LBB0_3:
	s_or_b64 exec, exec, s[0:1]
	s_waitcnt lgkmcnt(0)
	s_barrier
	s_getreg_b32 s0, hwreg(HW_REG_XCC_ID, 0, 4)
	s_and_b32 s4, s0, 15
	s_and_saveexec_b64 s[0:1], vcc
	s_cbranch_execz .LBB0_6
	s_mov_b64 s[2:3], exec
	v_mbcnt_lo_u32_b32 v1, s2, 0
	v_mbcnt_hi_u32_b32 v1, s3, v1
	v_cmp_eq_u32_e32 vcc, 0, v1
	s_and_b64 s[6:7], exec, vcc
	s_mov_b64 exec, s[6:7]
	s_cbranch_execz .LBB0_6
	s_lshl_b32 s6, s4, 8
	s_bcnt1_i32_b64 s2, s[2:3]
	v_mov_b32_e32 v1, s6
	v_mov_b32_e32 v2, s2
	global_atomic_add v1, v2, s[18:19] offset:1024
	s_getreg_b32 s6, hwreg(HW_REG_HW_ID)
	s_bfe_u32 s6, s6, 0x80008
	s_lshl_b32 s7, s4, 8
	s_or_b32 s6, s6, s7
	s_lshl_b32 s6, s6, 2
	s_add_u32 s6, s6, 0x8000
	v_mov_b32_e32 v1, s6
	v_mov_b32_e32 v2, 1
	global_atomic_add v3, v1, v2, s[18:19] sc0
	s_waitcnt vmcnt(0)
	v_readfirstlane_b32 s7, v3
	s_nop 1
	v_writelane_b32 v247, s7, 59
	v_writelane_b32 v247, s6, 60

.LBB0_652:
	s_add_i32 s26, s26, 1
	s_cmp_ge_i32 s26, s27
	s_mov_b64 s[0:1], -1
	s_cbranch_scc1 .LBB0_12
	v_readlane_b32 s2, v248, 43
	v_readlane_b32 s3, v248, 44
	s_and_b64 vcc, exec, s[2:3]
	s_cbranch_vccz .LBB0_703
	s_waitcnt vmcnt(0)
	s_waitcnt lgkmcnt(0)
	s_barrier
	s_mov_b64 s[2:3], exec
	v_readlane_b32 s0, v248, 45
	v_readlane_b32 s1, v248, 46
	s_and_b64 s[0:1], s[2:3], s[0:1]
	s_mov_b64 exec, s[0:1]
	s_cbranch_execz .Lbar_inv
	v_readlane_b32 s0, v247, 61
	s_cmp_eq_u32 s0, 0
	s_cbranch_scc1 .Lno_cu_inv
	buffer_inv sc1
	s_waitcnt vmcnt(0)
.Lno_cu_inv:
	s_mov_b64 s[0:1], src_shared_base
	v_mov_b32_e32 v157, s1
	s_waitcnt vmcnt(0) expcnt(0) lgkmcnt(0)
	v_readlane_b32 s0, v247, 57
	s_nop 1
	v_mov_b32_e32 v2, s0
	v_mov_b32_e32 v159, s1
	v_readlane_b32 s0, v247, 58
	s_nop 1
	v_mov_b32_e32 v0, s0
	s_waitcnt vmcnt(0) lgkmcnt(0)
	v_cmp_eq_u32_e32 vcc, 0, v2
	s_and_saveexec_b64 s[4:5], vcc
	s_cbranch_execz .LBB0_670
	s_mov_b32 s10, 1
	s_branch .LBB0_658

.Lbar_inv:
	v_readfirstlane_b32 s0, v167
	s_mov_b64 exec, s[2:3]
	s_cmp_eq_u32 s0, 64
	s_cbranch_scc0 .LBB0_702
	s_nop 0
	s_waitcnt vmcnt(0)
.LBB0_702:
	s_or_b64 exec, exec, s[2:3]
	v_readlane_b32 s0, v247, 62
	s_cmp_lg_u32 s0, 0
	s_cbranch_scc1 .Lcu_checked
	v_readlane_b32 s0, v247, 60
	s_mov_b32 s1, 1
	v_readlane_b32 vcc_lo, v247, 59
	v_mov_b32_e32 v0, s0
	global_load_dword v0, v0, s[18:19] sc1
	s_waitcnt vmcnt(0)
	v_readfirstlane_b32 s0, v0
	s_cmp_eq_u32 s0, 2
	s_cselect_b32 s0, 1, 0
	s_cmp_eq_u32 vcc_lo, 1
	s_cselect_b32 vcc_lo, 1, 0
	s_and_b32 s0, s0, vcc_lo
	s_xor_b32 s0, s0, 1
	v_writelane_b32 v247, s0, 61
	v_writelane_b32 v247, s1, 62
.Lcu_checked:
	s_mov_b64 s[0:1], 0
	s_waitcnt lgkmcnt(0)
	s_barrier
